# scan chunk loop edge: per-chunk address updates and counter hoisted above the chunk barrier
# speedup vs baseline: 1.0001x; 1.0001x over previous
; __device__ __forceinline__ void lds_barrier() { asm volatile("s_waitcnt lgkmcnt(0)" ::: "memory"); __builtin_amdgcn_s_barrier(); asm volatile("" ::: "memory"); }
; __device__ __forceinline__ void scan_phase(const Args& a, LAS unsigned char* lds, const bf16* Z, const float* W, const bf16* Aa, const bf16* KK, float* Y, int tid, int lane, int wave) {
;     ...
;                 yp[(size_t)(ch * SCH + j) * 512] = ykA;
;                 yp[(size_t)(ch * SCH + 16 + j) * 512] = ykB;
;             }
;             lds_barrier();
;         }
.LBB0_224:
	s_mov_b64 s[16:17], 0x8000
	s_add_i32 s22, s22, 1
	v_lshl_add_u64 v[172:173], v[172:173], 0, s[16:17]
	s_mov_b64 s[16:17], 0x10000
	s_mov_b64 s[20:21], 0x2c000
	v_lshl_add_u64 v[174:175], v[174:175], 0, s[16:17]
	v_lshl_add_u64 v[176:177], v[176:177], 0, s[20:21]
	v_lshl_add_u64 v[178:179], v[178:179], 0, s[20:21]
	s_cmpk_eq_i32 s22, 0x80
	v_lshl_add_u64 v[180:181], v[180:181], 0, s[16:17]
	s_waitcnt lgkmcnt(0)
	s_barrier
	s_cbranch_scc1 .LBB0_285
